# HGRN2 scan: state-update LDS reads (decay vector and K fragments) prefetched 8 deep through a register ring in both passes
# speedup vs baseline: 1.0005x; 1.0005x over previous
; template <int MODE>
; __device__ __forceinline__ void hg2_phase(const Params& p, char* shm, int wv) {
;     ...
;       } else if (tid < 128) dacc *= dd[tid];
;       _Pragma("unroll") for (int m = 0; m < 8; ++m) {
;         float4 dv = *(const float4*)&dd[16 * m + fq * 4];
;         S[m][0] *= dv.x; S[m][1] *= dv.y; S[m][2] *= dv.z; S[m][3] *= dv.w;
;         _Pragma("unroll") for (int k2 = 0; k2 < 2; ++k2) {
;           bf16x8 a = *(const bf16x8*)&Kd[(16 * m + fr) * KLD + k2 * 32 + fq * 8];
;           S[m] = __builtin_amdgcn_mfma_f32_16x16x32_bf16(a, vb[k2], S[m], 0, 0, 0);
;         }
;       }
;       if (c + 1 < 16) HG_STASH((c + 1) & 1);
.LBB0_2497:
	s_or_b64 exec, exec, s[14:15]
	v_add_u32_e32 v147, s16, v155
	ds_read_b128 v[194:197], v147 offset:63488
	ds_read_b128 v[198:201], v149 offset:17408
	ds_read_b128 v[202:205], v149 offset:17472
	ds_read_b128 v[206:209], v147 offset:63552
	ds_read_b128 v[210:213], v149 offset:19712
	ds_read_b128 v[214:217], v149 offset:19776
	ds_read_b128 v[218:221], v147 offset:63616
	ds_read_b128 v[222:225], v149 offset:22016
	v_add_u32_e32 v149, v147, v160
	s_add_i32 s13, s13, 1
	s_bitcmp1_b32 s13, 0
	s_cselect_b32 s14, 0xfa00, 0
	s_waitcnt lgkmcnt(7)
	v_pk_mul_f32 v[28:29], v[28:29], v[194:195]
	v_pk_mul_f32 v[30:31], v[30:31], v[196:197]
	ds_read_b128 v[194:197], v149 offset:22080
	s_add_i32 s16, s14, 0
	s_waitcnt lgkmcnt(7)
	v_mfma_f32_16x16x32_bf16 v[28:31], v[198:201], v[58:61], v[28:31]
	ds_read_b128 v[198:201], v147 offset:63680
	s_waitcnt lgkmcnt(7)
	v_mfma_f32_16x16x32_bf16 v[28:31], v[202:205], v[54:57], v[28:31]
	ds_read_b128 v[202:205], v149 offset:24320
	s_waitcnt lgkmcnt(7)
	v_pk_mul_f32 v[34:35], v[34:35], v[206:207]
	v_pk_mul_f32 v[36:37], v[36:37], v[208:209]
	ds_read_b128 v[206:209], v149 offset:24384
	s_waitcnt lgkmcnt(7)
	v_mfma_f32_16x16x32_bf16 v[34:37], v[210:213], v[58:61], v[34:37]
	ds_read_b128 v[210:213], v147 offset:63744
	s_waitcnt lgkmcnt(7)
	v_mfma_f32_16x16x32_bf16 v[34:37], v[214:217], v[54:57], v[34:37]
	ds_read_b128 v[214:217], v149 offset:26624
	s_waitcnt lgkmcnt(7)
	v_pk_mul_f32 v[20:21], v[20:21], v[218:219]
	v_pk_mul_f32 v[22:23], v[22:23], v[220:221]
	ds_read_b128 v[218:221], v149 offset:26688
	s_waitcnt lgkmcnt(7)
	v_mfma_f32_16x16x32_bf16 v[20:23], v[222:225], v[58:61], v[20:23]
	ds_read_b128 v[222:225], v147 offset:63808
	s_waitcnt lgkmcnt(7)
	v_mfma_f32_16x16x32_bf16 v[20:23], v[194:197], v[54:57], v[20:23]
	ds_read_b128 v[194:197], v149 offset:28928
	s_waitcnt lgkmcnt(7)
	v_pk_mul_f32 v[16:17], v[16:17], v[198:199]
	v_pk_mul_f32 v[18:19], v[18:19], v[200:201]
	ds_read_b128 v[198:201], v149 offset:28992
	s_waitcnt lgkmcnt(7)
	v_mfma_f32_16x16x32_bf16 v[16:19], v[202:205], v[58:61], v[16:19]
	ds_read_b128 v[202:205], v147 offset:63872
	s_waitcnt lgkmcnt(7)
	v_mfma_f32_16x16x32_bf16 v[16:19], v[206:209], v[54:57], v[16:19]
	ds_read_b128 v[206:209], v149 offset:31232
	s_waitcnt lgkmcnt(7)
	v_pk_mul_f32 v[12:13], v[12:13], v[210:211]
	v_pk_mul_f32 v[14:15], v[14:15], v[212:213]
	ds_read_b128 v[210:213], v149 offset:31296
	s_waitcnt lgkmcnt(7)
	v_mfma_f32_16x16x32_bf16 v[12:15], v[214:217], v[58:61], v[12:15]
	ds_read_b128 v[214:217], v147 offset:63936
	s_waitcnt lgkmcnt(7)
	v_mfma_f32_16x16x32_bf16 v[12:15], v[218:221], v[54:57], v[12:15]
	ds_read_b128 v[218:221], v149 offset:33536
	s_waitcnt lgkmcnt(7)
	v_pk_mul_f32 v[8:9], v[8:9], v[222:223]
	v_pk_mul_f32 v[10:11], v[10:11], v[224:225]
	s_nop 0
	s_waitcnt lgkmcnt(6)
	v_mfma_f32_16x16x32_bf16 v[8:11], v[194:197], v[58:61], v[8:11]
	s_waitcnt lgkmcnt(5)
	v_mfma_f32_16x16x32_bf16 v[8:11], v[198:201], v[54:57], v[8:11]
	s_waitcnt lgkmcnt(4)
	v_pk_mul_f32 v[4:5], v[4:5], v[202:203]
	v_pk_mul_f32 v[6:7], v[6:7], v[204:205]
	s_nop 0
	s_waitcnt lgkmcnt(3)
	v_mfma_f32_16x16x32_bf16 v[4:7], v[206:209], v[58:61], v[4:7]
	s_waitcnt lgkmcnt(2)
	v_mfma_f32_16x16x32_bf16 v[4:7], v[210:213], v[54:57], v[4:7]
	s_waitcnt lgkmcnt(1)
	v_pk_mul_f32 v[0:1], v[0:1], v[214:215]
	v_pk_mul_f32 v[2:3], v[2:3], v[216:217]
	s_nop 0
	s_waitcnt lgkmcnt(0)
	v_mfma_f32_16x16x32_bf16 v[0:3], v[218:221], v[58:61], v[0:3]
	ds_read_b128 v[58:61], v149 offset:33600
	s_waitcnt lgkmcnt(0)
	v_mfma_f32_16x16x32_bf16 v[0:3], v[58:61], v[54:57], v[0:3]
	v_lshl_add_u32 v54, v151, 1, s16
	v_add_u32_e32 v55, v54, v158
	s_waitcnt vmcnt(3)
	ds_write_b128 v55, v[42:45] offset:17408
	v_add_u32_e32 v42, v54, v159
	s_waitcnt vmcnt(2)
	ds_write_b128 v42, v[38:41] offset:17408
	s_waitcnt vmcnt(1)
	ds_write_b128 v55, v[46:49] offset:45056
	s_waitcnt vmcnt(0)
	ds_write_b128 v42, v[50:53] offset:45056
	s_and_saveexec_b64 s[14:15], vcc
	s_cbranch_execz .LBB0_2492
	v_add_u32_e32 v38, s16, v152
	ds_write_b128 v38, v[24:27] offset:63488
	s_branch .LBB0_2492

; __device__ __forceinline__ uint2 pack4(float a, float b, float c, float d) { uint2 r; r.x = pk2(a, b); r.y = pk2(c, d); return r; }
; template <int MODE>
; __device__ __forceinline__ void hg2_phase(const Params& p, char* shm, int wv) {
;     ...
;       if (MODE == 1) {
;         bf16x8 Sb[4];
;         _Pragma("unroll") for (int ks = 0; ks < 4; ++ks) {
;           uint2 lo = pack4(S[2 * ks][0], S[2 * ks][1], S[2 * ks][2], S[2 * ks][3]);
;           uint2 hi = pack4(S[2 * ks + 1][0], S[2 * ks + 1][1], S[2 * ks + 1][2], S[2 * ks + 1][3]);
;           uint4 pk; pk.x = lo.x; pk.y = lo.y; pk.z = hi.x; pk.w = hi.y; Sb[ks] = *(bf16x8*)&pk;
;         }
;         int tok0 = b * SEQ + cn * 64;
;         _Pragma("unroll") for (int rt = 0; rt < 4; ++rt) {
;           f32x4 o = {0.f, 0.f, 0.f, 0.f};
;           _Pragma("unroll") for (int ks = 0; ks < 4; ++ks) {
;             uint2 lo = *(const uint2*)&Qt[(16 * rt + fr) * QLD + 32 * ks + fq * 4];
;             uint2 hi = *(const uint2*)&Qt[(16 * rt + fr) * QLD + 32 * ks + 16 + fq * 4];
;             uint4 pk; pk.x = lo.x; pk.y = lo.y; pk.z = hi.x; pk.w = hi.y;
;             o = __builtin_amdgcn_mfma_f32_16x16x32_bf16(Sb[ks], *(bf16x8*)&pk, o, 0, 0, 0);
;           }
;           _Pragma("unroll") for (int k2 = 0; k2 < 2; ++k2) {
;             bf16x8 a = *(const bf16x8*)&At[(16 * rt + fr) * KLD + k2 * 32 + fq * 8];
;             o = __builtin_amdgcn_mfma_f32_16x16x32_bf16(vb[k2], a, o, 0, 0, 0);
;           }
;           *(uint2*)&qbuf[(long)(tok0 + 16 * rt + fr) * DM + h * 128 + 16 * wid + fq * 4] = pack4(o[0], o[1], o[2], o[3]);
;         }
.LBB0_2573:
	s_and_b32 s10, 1, s16
	s_cselect_b32 s11, 0, 0xfa00
	s_add_i32 s11, s11, 0
	v_add_u32_e32 v159, s11, v102
	v_add_u32_e32 v68, v159, v147
	v_add3_u32 v137, s11, v157, v158
	v_add3_u32 v161, s11, v158, v157
	ds_read_b128 v[72:75], v68 offset:45056
	ds_read_b128 v[68:71], v68 offset:45120
	ds_read2_b64 v[166:169], v137 offset1:8
	ds_read2_b64 v[170:173], v161 offset0:4 offset1:12
	v_cvt_pk_bf16_f32 v88, v28, v29
	v_cvt_pk_bf16_f32 v89, v30, v31
	v_cvt_pk_bf16_f32 v90, v4, v5
	v_cvt_pk_bf16_f32 v91, v6, v7
	v_cvt_pk_bf16_f32 v84, v16, v17
	v_cvt_pk_bf16_f32 v85, v18, v19
	v_cvt_pk_bf16_f32 v86, v8, v9
	v_cvt_pk_bf16_f32 v87, v10, v11
	s_waitcnt lgkmcnt(1)
	v_mov_b32_e32 v186, v166
	v_mov_b32_e32 v187, v167
	s_waitcnt lgkmcnt(0)
	v_mov_b32_e32 v188, v170
	v_mov_b32_e32 v189, v171
	v_mov_b32_e32 v170, v168
	v_mov_b32_e32 v171, v169
	v_mfma_f32_16x16x32_bf16 v[186:189], v[88:91], v[186:189], 0
	v_cvt_pk_bf16_f32 v80, v20, v21
	v_cvt_pk_bf16_f32 v81, v22, v23
	v_cvt_pk_bf16_f32 v82, v12, v13
	v_mfma_f32_16x16x32_bf16 v[166:169], v[84:87], v[170:173], v[186:189]
	ds_read2_b64 v[170:173], v137 offset0:16 offset1:24
	s_nop 2
	ds_read2_b64 v[186:189], v161 offset0:20 offset1:28
	v_cvt_pk_bf16_f32 v83, v14, v15
	v_cvt_pk_bf16_f32 v76, v24, v25
	v_cvt_pk_bf16_f32 v77, v26, v27
	v_cvt_pk_bf16_f32 v78, v0, v1
	v_cvt_pk_bf16_f32 v79, v2, v3
	s_waitcnt lgkmcnt(1)
	v_mov_b32_e32 v190, v170
	v_mov_b32_e32 v191, v171
	s_waitcnt lgkmcnt(0)
	v_mov_b32_e32 v192, v186
	v_mov_b32_e32 v193, v187
	v_add_u32_e32 v160, v159, v154
	v_mov_b32_e32 v186, v172
	v_mfma_f32_16x16x32_bf16 v[166:169], v[80:83], v[190:193], v[166:169]
	v_mov_b32_e32 v187, v173
	ds_read_b128 v[170:173], v160 offset:35840
	v_add_u32_e32 v136, s18, v32
	v_mfma_f32_16x16x32_bf16 v[166:169], v[76:79], v[186:189], v[166:169]
	v_ashrrev_i32_e32 v137, 31, v136
	s_andn2_b64 vcc, exec, s[6:7]
	s_waitcnt lgkmcnt(0)
	v_mfma_f32_16x16x32_bf16 v[166:169], v[72:75], v[170:173], v[166:169]
	ds_read_b128 v[170:173], v160 offset:35904
	s_waitcnt lgkmcnt(0)
	v_mfma_f32_16x16x32_bf16 v[166:169], v[68:71], v[170:173], v[166:169]
	s_nop 7
	v_cvt_pk_bf16_f32 v166, v166, v167
	v_cvt_pk_bf16_f32 v167, v168, v169
	v_lshlrev_b64 v[168:169], 11, v[136:137]
	v_lshl_add_u64 v[168:169], v[34:35], 0, v[168:169]
	v_add_u32_e32 v137, 0x1000, v161
	global_store_dwordx2 v[168:169], v[166:167], off
	ds_read2_b64 v[166:169], v137 offset0:32 offset1:36
	ds_read2_b64 v[170:173], v137 offset0:40 offset1:44
	s_waitcnt lgkmcnt(1)
	v_mfma_f32_16x16x32_bf16 v[166:169], v[88:91], v[166:169], 0
	s_waitcnt lgkmcnt(0)
	v_mfma_f32_16x16x32_bf16 v[166:169], v[84:87], v[170:173], v[166:169]
	ds_read2_b64 v[170:173], v137 offset0:48 offset1:52
	s_waitcnt lgkmcnt(0)
	v_mfma_f32_16x16x32_bf16 v[166:169], v[80:83], v[170:173], v[166:169]
	ds_read2_b64 v[170:173], v137 offset0:56 offset1:60
	v_add_u32_e32 v137, 0x2000, v161
	s_waitcnt lgkmcnt(0)
	v_mfma_f32_16x16x32_bf16 v[166:169], v[76:79], v[170:173], v[166:169]
	ds_read_b128 v[170:173], v160 offset:38144
	s_waitcnt lgkmcnt(0)
	v_mfma_f32_16x16x32_bf16 v[166:169], v[72:75], v[170:173], v[166:169]
	ds_read_b128 v[170:173], v160 offset:38208
	s_waitcnt lgkmcnt(0)
	v_mfma_f32_16x16x32_bf16 v[166:169], v[68:71], v[170:173], v[166:169]
	ds_read2_b64 v[170:173], v137 offset0:72 offset1:76
	s_nop 6
	v_cvt_pk_bf16_f32 v166, v166, v167
	v_cvt_pk_bf16_f32 v167, v168, v169
	v_add_u32_e32 v168, 16, v136
	v_ashrrev_i32_e32 v169, 31, v168
	v_lshlrev_b64 v[168:169], 11, v[168:169]
	v_lshl_add_u64 v[168:169], v[34:35], 0, v[168:169]
	global_store_dwordx2 v[168:169], v[166:167], off
	ds_read2_b64 v[166:169], v137 offset0:64 offset1:68
	s_waitcnt lgkmcnt(0)
	v_mfma_f32_16x16x32_bf16 v[166:169], v[88:91], v[166:169], 0
	v_mfma_f32_16x16x32_bf16 v[166:169], v[84:87], v[170:173], v[166:169]
	ds_read2_b64 v[170:173], v137 offset0:80 offset1:84
	s_waitcnt lgkmcnt(0)
	v_mfma_f32_16x16x32_bf16 v[166:169], v[80:83], v[170:173], v[166:169]
	ds_read2_b64 v[170:173], v137 offset0:88 offset1:92
	v_add_u32_e32 v137, 0x3000, v161
	s_waitcnt lgkmcnt(0)
	v_mfma_f32_16x16x32_bf16 v[166:169], v[76:79], v[170:173], v[166:169]
	ds_read_b128 v[170:173], v160 offset:40448
	s_waitcnt lgkmcnt(0)
	v_mfma_f32_16x16x32_bf16 v[166:169], v[72:75], v[170:173], v[166:169]
	ds_read_b128 v[170:173], v160 offset:40512
	s_waitcnt lgkmcnt(0)
	v_mfma_f32_16x16x32_bf16 v[166:169], v[68:71], v[170:173], v[166:169]
	s_nop 7
	v_cvt_pk_bf16_f32 v166, v166, v167
	v_cvt_pk_bf16_f32 v167, v168, v169
	v_add_u32_e32 v168, 32, v136
	v_ashrrev_i32_e32 v169, 31, v168
	v_lshlrev_b64 v[168:169], 11, v[168:169]
	v_lshl_add_u64 v[168:169], v[34:35], 0, v[168:169]
	global_store_dwordx2 v[168:169], v[166:167], off
	ds_read2_b64 v[166:169], v137 offset0:96 offset1:100
	s_waitcnt lgkmcnt(0)
	v_mfma_f32_16x16x32_bf16 v[88:91], v[88:91], v[166:169], 0
	ds_read2_b64 v[166:169], v137 offset0:104 offset1:108
	s_waitcnt lgkmcnt(0)
	v_mfma_f32_16x16x32_bf16 v[84:87], v[84:87], v[166:169], v[88:91]
	s_nop 4
	ds_read2_b64 v[88:91], v137 offset0:112 offset1:116
	s_waitcnt lgkmcnt(0)
; __device__ __forceinline__ uint2 pack4(float a, float b, float c, float d) { uint2 r; r.x = pk2(a, b); r.y = pk2(c, d); return r; }
; template <int MODE>
; __device__ __forceinline__ void hg2_phase(const Params& p, char* shm, int wv) {
;     ...
;           _Pragma("unroll") for (int k2 = 0; k2 < 2; ++k2) {
;             bf16x8 a = *(const bf16x8*)&At[(16 * rt + fr) * KLD + k2 * 32 + fq * 8];
;             o = __builtin_amdgcn_mfma_f32_16x16x32_bf16(vb[k2], a, o, 0, 0, 0);
;           }
;           *(uint2*)&qbuf[(long)(tok0 + 16 * rt + fr) * DM + h * 128 + 16 * wid + fq * 4] = pack4(o[0], o[1], o[2], o[3]);
;         }
;       } else if (tid < 128) dacc *= dd[tid];
;       _Pragma("unroll") for (int m = 0; m < 8; ++m) {
;         float4 dv = *(const float4*)&dd[16 * m + fq * 4];
;         S[m][0] *= dv.x; S[m][1] *= dv.y; S[m][2] *= dv.z; S[m][3] *= dv.w;
;         _Pragma("unroll") for (int k2 = 0; k2 < 2; ++k2) {
;           bf16x8 a = *(const bf16x8*)&Kd[(16 * m + fr) * KLD + k2 * 32 + fq * 8];
;           S[m] = __builtin_amdgcn_mfma_f32_16x16x32_bf16(a, vb[k2], S[m], 0, 0, 0);
;         }
;       }
;       if (c + 1 < 16) HG_STASH((c + 1) & 1);
	v_mfma_f32_16x16x32_bf16 v[80:83], v[80:83], v[88:91], v[84:87]
	s_nop 2
	ds_read2_b64 v[84:87], v137 offset0:120 offset1:124
	s_waitcnt lgkmcnt(0)
	v_mfma_f32_16x16x32_bf16 v[76:79], v[76:79], v[84:87], v[80:83]
	s_nop 2
	ds_read_b128 v[80:83], v160 offset:42752
	s_waitcnt lgkmcnt(0)
	v_mfma_f32_16x16x32_bf16 v[76:79], v[72:75], v[80:83], v[76:79]
	ds_read_b128 v[80:83], v160 offset:42816
	s_waitcnt lgkmcnt(0)
	v_mfma_f32_16x16x32_bf16 v[76:79], v[68:71], v[80:83], v[76:79]
	s_nop 7
	v_cvt_pk_bf16_f32 v76, v76, v77
	v_cvt_pk_bf16_f32 v77, v78, v79
	v_add_u32_e32 v78, 48, v136
	v_ashrrev_i32_e32 v79, 31, v78
	v_lshlrev_b64 v[78:79], 11, v[78:79]
	v_lshl_add_u64 v[78:79], v[34:35], 0, v[78:79]
	global_store_dwordx2 v[78:79], v[76:77], off
	ds_read_b128 v[194:197], v159 offset:63488
	ds_read_b128 v[198:201], v160 offset:17408
	ds_read_b128 v[202:205], v160 offset:17472
	ds_read_b128 v[206:209], v159 offset:63552
	ds_read_b128 v[210:213], v160 offset:19712
	ds_read_b128 v[214:217], v160 offset:19776
	ds_read_b128 v[218:221], v159 offset:63616
	ds_read_b128 v[222:225], v160 offset:22016
	s_waitcnt lgkmcnt(7)
	v_pk_mul_f32 v[28:29], v[28:29], v[194:195]
	v_pk_mul_f32 v[30:31], v[30:31], v[196:197]
	ds_read_b128 v[194:197], v160 offset:22080
	s_waitcnt lgkmcnt(7)
	v_mfma_f32_16x16x32_bf16 v[28:31], v[198:201], v[72:75], v[28:31]
	ds_read_b128 v[198:201], v159 offset:63680
	s_waitcnt lgkmcnt(7)
	v_mfma_f32_16x16x32_bf16 v[28:31], v[202:205], v[68:71], v[28:31]
	ds_read_b128 v[202:205], v160 offset:24320
	s_waitcnt lgkmcnt(7)
	v_pk_mul_f32 v[4:5], v[4:5], v[206:207]
	v_pk_mul_f32 v[6:7], v[6:7], v[208:209]
	ds_read_b128 v[206:209], v160 offset:24384
	s_waitcnt lgkmcnt(7)
	v_mfma_f32_16x16x32_bf16 v[4:7], v[210:213], v[72:75], v[4:7]
	ds_read_b128 v[210:213], v159 offset:63744
	s_waitcnt lgkmcnt(7)
	v_mfma_f32_16x16x32_bf16 v[4:7], v[214:217], v[68:71], v[4:7]
	ds_read_b128 v[214:217], v160 offset:26624
	s_waitcnt lgkmcnt(7)
	v_pk_mul_f32 v[16:17], v[16:17], v[218:219]
	v_pk_mul_f32 v[18:19], v[18:19], v[220:221]
	ds_read_b128 v[218:221], v160 offset:26688
	s_waitcnt lgkmcnt(7)
	v_mfma_f32_16x16x32_bf16 v[16:19], v[222:225], v[72:75], v[16:19]
	ds_read_b128 v[222:225], v159 offset:63808
	s_waitcnt lgkmcnt(7)
	v_mfma_f32_16x16x32_bf16 v[16:19], v[194:197], v[68:71], v[16:19]
	ds_read_b128 v[194:197], v160 offset:28928
	s_waitcnt lgkmcnt(7)
	v_pk_mul_f32 v[8:9], v[8:9], v[198:199]
	v_pk_mul_f32 v[10:11], v[10:11], v[200:201]
	ds_read_b128 v[198:201], v160 offset:28992
	s_waitcnt lgkmcnt(7)
	v_mfma_f32_16x16x32_bf16 v[8:11], v[202:205], v[72:75], v[8:11]
	ds_read_b128 v[202:205], v159 offset:63872
	s_waitcnt lgkmcnt(7)
	v_mfma_f32_16x16x32_bf16 v[8:11], v[206:209], v[68:71], v[8:11]
	ds_read_b128 v[206:209], v160 offset:31232
	s_waitcnt lgkmcnt(7)
	v_pk_mul_f32 v[20:21], v[20:21], v[210:211]
	v_pk_mul_f32 v[22:23], v[22:23], v[212:213]
	ds_read_b128 v[210:213], v160 offset:31296
	s_waitcnt lgkmcnt(7)
	v_mfma_f32_16x16x32_bf16 v[20:23], v[214:217], v[72:75], v[20:23]
	ds_read_b128 v[214:217], v159 offset:63936
	s_waitcnt lgkmcnt(7)
	v_mfma_f32_16x16x32_bf16 v[20:23], v[218:221], v[68:71], v[20:23]
	ds_read_b128 v[218:221], v160 offset:33536
	s_waitcnt lgkmcnt(7)
	v_pk_mul_f32 v[12:13], v[12:13], v[222:223]
	v_pk_mul_f32 v[14:15], v[14:15], v[224:225]
	s_nop 0
	s_waitcnt lgkmcnt(6)
	v_mfma_f32_16x16x32_bf16 v[12:15], v[194:197], v[72:75], v[12:15]
	s_waitcnt lgkmcnt(5)
	v_mfma_f32_16x16x32_bf16 v[12:15], v[198:201], v[68:71], v[12:15]
	s_waitcnt lgkmcnt(4)
	v_pk_mul_f32 v[24:25], v[24:25], v[202:203]
	v_pk_mul_f32 v[26:27], v[26:27], v[204:205]
	s_nop 0
	s_waitcnt lgkmcnt(3)
	v_mfma_f32_16x16x32_bf16 v[24:27], v[206:209], v[72:75], v[24:27]
	s_waitcnt lgkmcnt(2)
	v_mfma_f32_16x16x32_bf16 v[24:27], v[210:213], v[68:71], v[24:27]
	s_waitcnt lgkmcnt(1)
	v_pk_mul_f32 v[0:1], v[0:1], v[214:215]
	v_pk_mul_f32 v[2:3], v[2:3], v[216:217]
	s_nop 0
	s_waitcnt lgkmcnt(0)
	v_mfma_f32_16x16x32_bf16 v[0:3], v[218:221], v[72:75], v[0:3]
	ds_read_b128 v[72:75], v160 offset:33600
	s_waitcnt lgkmcnt(0)
	v_mfma_f32_16x16x32_bf16 v[0:3], v[72:75], v[68:71], v[0:3]
	s_cbranch_vccnz .LBB0_2568
	s_cmp_eq_u32 s10, 1
	s_cselect_b32 s6, 0xfa00, 0
	s_add_i32 s10, s6, 0
	v_lshl_add_u32 v68, v140, 1, s10
	v_add_u32_e32 v69, v68, v150
	v_add_u32_e32 v68, v68, v151
	s_waitcnt vmcnt(10)
	ds_write_b128 v69, v[36:39]
	s_waitcnt vmcnt(9)
	ds_write_b128 v68, v[40:43]
	v_lshl_add_u32 v68, v141, 1, s10
	v_add_u32_e32 v69, v68, v152
	v_add_u32_e32 v70, v68, v153
	v_lshl_add_u32 v68, v145, 1, v68
	s_waitcnt vmcnt(8)
	ds_write_b128 v69, v[44:47] offset:17408
	s_waitcnt vmcnt(7)
	ds_write_b128 v70, v[48:51] offset:17408
	s_waitcnt vmcnt(6)
	ds_write_b128 v68, v[56:59] offset:35840
	s_waitcnt vmcnt(5)
	ds_write_b128 v69, v[60:63] offset:45056
	s_waitcnt vmcnt(4)
	ds_write_b128 v70, v[64:67] offset:45056
	s_and_saveexec_b64 s[6:7], s[4:5]
	s_cbranch_execz .LBB0_2567
	v_add_u32_e32 v68, s10, v142
	ds_write_b128 v68, v[52:55] offset:63488
	s_branch .LBB0_2567
